# S1: short-conv row loads prefetched up front (28 loads in flight instead of 12 serialized round trips); dt_acum barrier moved to just before the s_w reads so waves 4-7 start their loads immediately
# speedup vs baseline: 1.0080x; 1.0080x over previous
; __device__ __forceinline__ const float* inp(const Params& p, int i) { asm volatile("" : "+s"(i)); return p.in[i]; }
; __device__ __forceinline__ float bfv(const u32x4& v, int j) { const unsigned w = v[j >> 1]; return (j & 1) ? bf_hi(w) : bf_lo(w); }
; __device__ void phase_s1(const Params& p, int layer, unsigned char* lds) {
;     ...
;             const int t2 = tid - 384, rr = t2 & 7, cgi = t2 >> 3, l0 = rr * 8, ch0 = g * 128 + cgi * 8;
;             const float* scw = inp(p, 11) + (size_t)layer * 3 * 1024 + ch0;
;             float w[3][8];
; #pragma unroll
;             for (int k = 0; k < 3; ++k) { const f32x4 a = *(const f32x4*)(scw + k * 1024), bb = *(const f32x4*)(scw + k * 1024 + 4);
; #pragma unroll
;                 for (int j = 0; j < 4; ++j) { w[k][j] = a[j]; w[k][4 + j] = bb[j]; } }
;             float um2[8], um1[8], u0[8];
; #pragma unroll
;             for (int i = 0; i < 10; ++i) {
;                 const int lrow = l0 - 2 + i;
; #pragma unroll
;                 for (int j = 0; j < 8; ++j) { um2[j] = um1[j]; um1[j] = u0[j]; }
;                 if (lrow >= 0 || (c > 0 && c < NPCH)) {
;                     const bf16_t* rp = proj + (size_t)(row0 + lrow) * PROJ_LD + ch0;
;                     const u32x4 cv = *(const u32x4*)(rp + 1024), xv = *(const u32x4*)(rp + 2048);
; #pragma unroll
;                     for (int j = 0; j < 8; ++j) u0[j] = bfv(cv, j) * bfv(xv, j);
.LBB0_334:
	s_or_b64 exec, exec, s[64:65]
	s_and_saveexec_b64 s[4:5], s[54:55]
	s_xor_b64 s[80:81], exec, s[4:5]
	s_cbranch_execz .LBB0_350
	s_mov_b32 s4, 11
	s_ashr_i32 s5, s4, 31
	s_lshl_b64 s[4:5], s[4:5], 3
	s_add_u32 s4, s0, s4
	s_addc_u32 s5, s1, s5
	s_load_dwordx2 s[4:5], s[4:5], 0x0
	s_mul_i32 s28, s12, 0x3000
	v_lshl_add_u32 v132, s2, 7, v111
	v_sub_co_u32_e64 v28, s[64:65], s87, v171
	s_waitcnt lgkmcnt(0)
	s_add_u32 s4, s4, s28
	s_mul_hi_i32 s28, s12, 0x3000
	s_addc_u32 s5, s5, s28
	v_lshl_add_u64 v[4:5], v[132:133], 2, s[4:5]
	s_mov_b64 s[4:5], 0x1000
	v_lshl_add_u64 v[6:7], v[4:5], 0, s[4:5]
	s_movk_i32 s4, 0x2000
	v_add_co_u32_e32 v8, vcc, s4, v4
	s_mov_b64 s[4:5], 0x2000
	global_load_dwordx4 v[12:15], v[4:5], off offset:16
	global_load_dwordx4 v[16:19], v[4:5], off
	v_addc_co_u32_e32 v9, vcc, 0, v5, vcc
	v_lshl_add_u64 v[4:5], v[4:5], 0, s[4:5]
	global_load_dwordx4 v[24:27], v[8:9], off offset:-4096
	s_nop 0
	global_load_dwordx4 v[8:11], v[8:9], off
	s_nop 0
	global_load_dwordx4 v[20:23], v[6:7], off offset:16
	s_nop 0
	global_load_dwordx4 v[4:7], v[4:5], off offset:16
	v_readlane_b32 s98, v252, 19
	v_readlane_b32 s99, v252, 20
	v_add_u32_e32 v100, s21, v113
	s_nop 1
	v_lshl_add_u64 v[102:103], v[132:133], 1, s[98:99]
	s_mov_b64 s[100:101], 0x4800
	v_mad_i64_i32 v[100:101], vcc, v100, s35, v[102:103]
	v_add_co_u32_e32 v102, vcc, s36, v100
	s_nop 1
	v_addc_co_u32_e32 v103, vcc, 0, v101, vcc
	global_load_dwordx4 v[172:175], v[100:101], off offset:2048
	global_load_dwordx4 v[212:215], v[102:103], off
	v_lshl_add_u64 v[100:101], v[100:101], 0, s[100:101]
	v_lshl_add_u64 v[102:103], v[102:103], 0, s[100:101]
	global_load_dwordx4 v[176:179], v[100:101], off offset:2048
	global_load_dwordx4 v[216:219], v[102:103], off
	v_lshl_add_u64 v[100:101], v[100:101], 0, s[100:101]
	v_lshl_add_u64 v[102:103], v[102:103], 0, s[100:101]
	global_load_dwordx4 v[180:183], v[100:101], off offset:2048
	global_load_dwordx4 v[220:223], v[102:103], off
	global_load_dwordx4 v[144:147], v[100:101], off
	v_lshl_add_u64 v[100:101], v[100:101], 0, s[100:101]
	v_lshl_add_u64 v[102:103], v[102:103], 0, s[100:101]
	global_load_dwordx4 v[184:187], v[100:101], off offset:2048
	global_load_dwordx4 v[224:227], v[102:103], off
	global_load_dwordx4 v[148:151], v[100:101], off
	v_lshl_add_u64 v[100:101], v[100:101], 0, s[100:101]
	v_lshl_add_u64 v[102:103], v[102:103], 0, s[100:101]
	global_load_dwordx4 v[188:191], v[100:101], off offset:2048
	global_load_dwordx4 v[228:231], v[102:103], off
	global_load_dwordx4 v[152:155], v[100:101], off
	v_lshl_add_u64 v[100:101], v[100:101], 0, s[100:101]
	v_lshl_add_u64 v[102:103], v[102:103], 0, s[100:101]
	global_load_dwordx4 v[192:195], v[100:101], off offset:2048
	global_load_dwordx4 v[232:235], v[102:103], off
	global_load_dwordx4 v[156:159], v[100:101], off
	v_lshl_add_u64 v[100:101], v[100:101], 0, s[100:101]
	v_lshl_add_u64 v[102:103], v[102:103], 0, s[100:101]
	global_load_dwordx4 v[196:199], v[100:101], off offset:2048
	global_load_dwordx4 v[236:239], v[102:103], off
	global_load_dwordx4 v[72:75], v[100:101], off
	v_lshl_add_u64 v[100:101], v[100:101], 0, s[100:101]
	v_lshl_add_u64 v[102:103], v[102:103], 0, s[100:101]
	global_load_dwordx4 v[200:203], v[100:101], off offset:2048
	global_load_dwordx4 v[240:243], v[102:103], off
	global_load_dwordx4 v[76:79], v[100:101], off
	v_lshl_add_u64 v[100:101], v[100:101], 0, s[100:101]
	v_lshl_add_u64 v[102:103], v[102:103], 0, s[100:101]
	global_load_dwordx4 v[204:207], v[100:101], off offset:2048
	global_load_dwordx4 v[244:247], v[102:103], off
	global_load_dwordx4 v[80:83], v[100:101], off
	v_lshl_add_u64 v[100:101], v[100:101], 0, s[100:101]
	v_lshl_add_u64 v[102:103], v[102:103], 0, s[100:101]
	global_load_dwordx4 v[208:211], v[100:101], off offset:2048
	global_load_dwordx4 v[140:143], v[102:103], off
	global_load_dwordx4 v[84:87], v[100:101], off
	s_add_i32 s4, s87, -1
	s_cmpk_gt_u32 s4, 0x7e
	s_cselect_b64 s[4:5], -1, 0
	s_cmp_gt_u32 s86, 7
	v_ashrrev_i32_e32 v29, 31, v28
	s_cselect_b64 s[66:67], -1, 0
	v_readfirstlane_b32 s29, v28
	v_lshl_add_u64 v[28:29], s[70:71], 0, v[28:29]
	v_lshlrev_b64 v[46:47], 13, v[28:29]
	s_xor_b64 s[52:53], s[58:59], -1
	v_cndmask_b32_e64 v28, 0, 1, s[66:67]
	s_and_b64 s[52:53], s[52:53], s[4:5]
	v_cmp_ne_u32_e64 s[66:67], 1, v28
	s_waitcnt vmcnt(0)
	s_and_saveexec_b64 s[4:5], s[52:53]
	s_xor_b64 s[4:5], exec, s[4:5]
	s_cbranch_execz .LBB0_338
	v_mov_b32_e32 v39, 0
	s_and_b64 vcc, exec, s[66:67]
	v_mov_b32_e32 v38, 0
	v_mov_b32_e32 v37, 0
	v_mov_b32_e32 v36, 0
	v_mov_b32_e32 v43, 0
	v_mov_b32_e32 v42, 0
	v_mov_b32_e32 v41, 0
	v_mov_b32_e32 v40, 0
	s_cbranch_vccnz .LBB0_338
	s_mov_b32 s82, 2
	s_ashr_i32 s83, s82, 31
	s_lshl_b64 s[82:83], s[82:83], 3
	s_add_u32 s82, s0, s82
	s_addc_u32 s83, s1, s83
	s_load_dwordx2 s[82:83], s[82:83], 0x0
	s_waitcnt lgkmcnt(0)
	v_lshl_add_u64 v[28:29], s[82:83], 0, v[46:47]
	v_lshl_add_u64 v[28:29], v[132:133], 2, v[28:29]
	global_load_dwordx4 v[40:43], v[28:29], off
	global_load_dwordx4 v[36:39], v[28:29], off offset:16
.LBB0_338:
	s_or_saveexec_b64 s[4:5], s[4:5]
	v_readlane_b32 s82, v252, 19
	v_readlane_b32 s83, v252, 20
	s_nop 1
	v_lshl_add_u64 v[44:45], v[132:133], 1, s[82:83]
	s_xor_b64 exec, exec, s[4:5]
	s_cbranch_execz .LBB0_340
	v_add_u32_e32 v28, s21, v113
	v_mad_i64_i32 v[32:33], s[82:83], v28, s35, v[44:45]
	v_mov_b64_e32 v[28:29], v[172:173]
	v_mov_b64_e32 v[30:31], v[174:175]
	v_add_co_u32_e32 v32, vcc, 0x1000, v32
	s_waitcnt vmcnt(0)
	v_lshlrev_b32_e32 v40, 16, v28
	v_addc_co_u32_e32 v33, vcc, 0, v33, vcc
	v_mov_b64_e32 v[32:33], v[212:213]
	v_mov_b64_e32 v[34:35], v[214:215]
	v_and_b32_e32 v41, 0xffff0000, v28
	v_lshlrev_b32_e32 v28, 16, v29
	v_and_b32_e32 v29, 0xffff0000, v29
	v_lshlrev_b32_e32 v36, 16, v30
	v_and_b32_e32 v37, 0xffff0000, v30
	v_lshlrev_b32_e32 v30, 16, v31
	v_and_b32_e32 v31, 0xffff0000, v31
	s_waitcnt vmcnt(0)
	v_lshlrev_b32_e32 v48, 16, v32
	v_and_b32_e32 v49, 0xffff0000, v32
	v_lshlrev_b32_e32 v32, 16, v33
	v_and_b32_e32 v33, 0xffff0000, v33
	v_lshlrev_b32_e32 v42, 16, v34
	v_and_b32_e32 v43, 0xffff0000, v34
	v_lshlrev_b32_e32 v34, 16, v35
	v_and_b32_e32 v35, 0xffff0000, v35
	v_pk_mul_f32 v[38:39], v[30:31], v[34:35]
	v_pk_mul_f32 v[36:37], v[36:37], v[42:43]
	v_pk_mul_f32 v[42:43], v[28:29], v[32:33]
	v_pk_mul_f32 v[40:41], v[40:41], v[48:49]

; __device__ __forceinline__ const float* inp(const Params& p, int i) { asm volatile("" : "+s"(i)); return p.in[i]; }
; __device__ __forceinline__ unsigned cvt_pk_bf16(float lo, float hi) { f32x2 v = {lo, hi}; bf16x2v b = __builtin_convertvector(v, bf16x2v); return __builtin_bit_cast(unsigned, b); }
; __device__ __forceinline__ float bfv(const u32x4& v, int j) { const unsigned w = v[j >> 1]; return (j & 1) ? bf_hi(w) : bf_lo(w); }
; __device__ void phase_s1(const Params& p, int layer, unsigned char* lds) {
;     ...
; #pragma unroll
;             for (int i = 0; i < 10; ++i) {
;                 const int lrow = l0 - 2 + i;
; #pragma unroll
;                 for (int j = 0; j < 8; ++j) { um2[j] = um1[j]; um1[j] = u0[j]; }
;                 if (lrow >= 0 || (c > 0 && c < NPCH)) {
;                     const bf16_t* rp = proj + (size_t)(row0 + lrow) * PROJ_LD + ch0;
;                     const u32x4 cv = *(const u32x4*)(rp + 1024), xv = *(const u32x4*)(rp + 2048);
; #pragma unroll
;                     for (int j = 0; j < 8; ++j) u0[j] = bfv(cv, j) * bfv(xv, j);
;                 } else if (c == 0) {
; #pragma unroll
;                     for (int j = 0; j < 8; ++j) u0[j] = 0.f;
;                 } else {
;                     const float* hp = inp(p, 2) + (((size_t)layer * 8 + (c - NPCH)) * 2 + (2 + lrow)) * 1024 + ch0;
;                     const f32x4 a = *(const f32x4*)hp, bb = *(const f32x4*)(hp + 4);
; #pragma unroll
;                     for (int j = 0; j < 4; ++j) { u0[j] = a[j]; u0[4 + j] = bb[j]; }
;                 }
;                 if (i >= 2) {
;                     const int l = l0 + i - 2;
;                     const u32x4 bv = *(const u32x4*)(proj + (size_t)(row0 + l) * PROJ_LD + ch0);
;                     float y[8];
; #pragma unroll
;                     for (int j = 0; j < 8; ++j) y[j] = bfv(bv, j) * (w[0][j] * um2[j] + w[1][j] * um1[j] + w[2][j] * u0[j]);
;                     u32x4 pk; pk.x = cvt_pk_bf16(y[0], y[1]); pk.y = cvt_pk_bf16(y[2], y[3]); pk.z = cvt_pk_bf16(y[4], y[5]); pk.w = cvt_pk_bf16(y[6], y[7]);
;                     *(u32x4*)(mix + pg8::img_off(row0 + l, ch0, D_MIX / 64)) = pk;
.LBB0_343:
	s_andn2_saveexec_b64 s[4:5], s[4:5]
	s_cbranch_execz .LBB0_345
	s_waitcnt vmcnt(0)
	v_add_u32_e32 v28, s21, v122
	v_mad_i64_i32 v[32:33], s[52:53], v28, s35, v[44:45]
	v_mov_b64_e32 v[28:29], v[176:177]
	v_mov_b64_e32 v[30:31], v[178:179]
	v_add_co_u32_e32 v32, vcc, 0x1000, v32
	s_waitcnt vmcnt(0)
	v_lshlrev_b32_e32 v46, 16, v28
	v_addc_co_u32_e32 v33, vcc, 0, v33, vcc
	v_mov_b64_e32 v[32:33], v[216:217]
	v_mov_b64_e32 v[34:35], v[218:219]
	v_and_b32_e32 v47, 0xffff0000, v28
	v_lshlrev_b32_e32 v48, 16, v29
	v_and_b32_e32 v49, 0xffff0000, v29
	v_lshlrev_b32_e32 v28, 16, v30
	v_and_b32_e32 v29, 0xffff0000, v30
	v_lshlrev_b32_e32 v30, 16, v31
	v_and_b32_e32 v31, 0xffff0000, v31
	s_waitcnt vmcnt(0)
	v_lshlrev_b32_e32 v50, 16, v32
	v_and_b32_e32 v51, 0xffff0000, v32
	v_lshlrev_b32_e32 v32, 16, v33
	v_and_b32_e32 v33, 0xffff0000, v33
	v_lshlrev_b32_e32 v52, 16, v34
	v_and_b32_e32 v53, 0xffff0000, v34
	v_lshlrev_b32_e32 v34, 16, v35
	v_and_b32_e32 v35, 0xffff0000, v35
	v_pk_mul_f32 v[30:31], v[30:31], v[34:35]
	v_pk_mul_f32 v[28:29], v[28:29], v[52:53]
	v_pk_mul_f32 v[34:35], v[48:49], v[32:33]
	v_pk_mul_f32 v[32:33], v[46:47], v[50:51]
.LBB0_345:
	s_or_b64 exec, exec, s[4:5]
	s_add_i32 s28, s21, -2
	s_add_u32 s4, s70, s29
	s_addc_u32 s5, s71, 0
	v_or_b32_e32 v46, s21, v112
	s_lshl_b64 s[66:67], s[4:5], 13
	v_mad_i64_i32 v[50:51], s[4:5], v46, s35, v[44:45]
	v_mov_b64_e32 v[46:47], v[180:181]
	v_mov_b64_e32 v[48:49], v[182:183]
	v_add_co_u32_e32 v50, vcc, s36, v50
	v_add_u32_e32 v60, s28, v123
	s_nop 0
	v_addc_co_u32_e32 v51, vcc, 0, v51, vcc
	v_mov_b64_e32 v[56:57], v[220:221]
	v_mov_b64_e32 v[58:59], v[222:223]
	v_mad_i64_i32 v[50:51], s[4:5], v60, s35, v[44:45]
	v_mov_b64_e32 v[64:65], v[144:145]
	v_mov_b64_e32 v[66:67], v[146:147]
	v_pk_mul_f32 v[54:55], v[24:25], v[32:33]
	v_ashrrev_i32_e32 v62, 6, v132
	v_pk_fma_f32 v[40:41], v[16:17], v[40:41], v[54:55]
	s_movk_i32 s4, 0x200
	v_readlane_b32 s52, v252, 21
	v_readlane_b32 s53, v252, 22
	v_add_u32_e32 v63, s28, v130
	s_cmpk_gt_i32 s87, 0x7e
	s_cselect_b64 s[82:83], -1, 0
	v_lshlrev_b32_e32 v50, 16, v46
	v_and_b32_e32 v51, 0xffff0000, v46
	v_lshlrev_b32_e32 v46, 16, v47
	v_and_b32_e32 v47, 0xffff0000, v47
	v_lshlrev_b32_e32 v52, 16, v56
	v_and_b32_e32 v53, 0xffff0000, v56
	v_pk_mul_f32 v[52:53], v[50:51], v[52:53]
	v_lshlrev_b32_e32 v50, 16, v64
	v_and_b32_e32 v51, 0xffff0000, v64
	v_pk_fma_f32 v[40:41], v[8:9], v[52:53], v[40:41]
	s_nop 0
	v_pk_mul_f32 v[40:41], v[40:41], v[50:51]
	v_lshlrev_b32_e32 v50, 16, v57
	v_and_b32_e32 v51, 0xffff0000, v57
	v_pk_mul_f32 v[54:55], v[46:47], v[50:51]
	v_pk_mul_f32 v[50:51], v[26:27], v[34:35]
	v_lshlrev_b32_e32 v46, 16, v65
	v_pk_fma_f32 v[42:43], v[18:19], v[42:43], v[50:51]
	v_and_b32_e32 v47, 0xffff0000, v65
	v_pk_fma_f32 v[42:43], v[10:11], v[54:55], v[42:43]
	v_lshlrev_b32_e32 v50, 16, v58
	v_pk_mul_f32 v[42:43], v[42:43], v[46:47]
	v_lshlrev_b32_e32 v46, 16, v48
	v_and_b32_e32 v47, 0xffff0000, v48
	v_and_b32_e32 v51, 0xffff0000, v58
	v_pk_mul_f32 v[56:57], v[46:47], v[50:51]
	v_pk_mul_f32 v[50:51], v[20:21], v[28:29]
	v_lshlrev_b32_e32 v46, 16, v66
	v_pk_fma_f32 v[36:37], v[12:13], v[36:37], v[50:51]
	v_and_b32_e32 v47, 0xffff0000, v66
	v_pk_fma_f32 v[36:37], v[4:5], v[56:57], v[36:37]
	v_lshlrev_b32_e32 v48, 16, v59
	v_pk_mul_f32 v[46:47], v[36:37], v[46:47]
	v_lshlrev_b32_e32 v36, 16, v49
	v_and_b32_e32 v37, 0xffff0000, v49
	v_and_b32_e32 v49, 0xffff0000, v59
	v_pk_mul_f32 v[58:59], v[36:37], v[48:49]
	v_pk_mul_f32 v[48:49], v[22:23], v[30:31]
	v_lshlrev_b32_e32 v36, 16, v67
	v_pk_fma_f32 v[38:39], v[14:15], v[38:39], v[48:49]
	v_and_b32_e32 v37, 0xffff0000, v67
	v_pk_fma_f32 v[38:39], v[6:7], v[58:59], v[38:39]
	v_pk_mul_f32 v[50:51], v[24:25], v[52:53]
	v_pk_mul_f32 v[48:49], v[38:39], v[36:37]
	v_cvt_pk_bf16_f32 v36, v40, v41
	v_cvt_pk_bf16_f32 v37, v42, v43
	v_lshrrev_b32_e32 v40, 8, v60
	v_lshrrev_b32_e32 v43, 3, v60
	v_cvt_pk_bf16_f32 v38, v46, v47
	v_mad_i32_i24 v40, v40, 48, v62
	v_lshlrev_b32_e32 v42, 6, v60
	v_and_or_b32 v43, v43, 14, v114
	v_lshlrev_b32_e32 v46, 2, v60
	v_ashrrev_i32_e32 v41, 31, v40
	v_and_or_b32 v42, v42, s4, v115
	v_lshlrev_b32_e32 v43, 10, v43
	v_and_b32_e32 v46, 32, v46
	v_bitop3_b32 v42, v42, v43, v46 bitop3:0xde
	v_lshlrev_b64 v[40:41], 15, v[40:41]
	v_lshlrev_b32_e32 v46, 7, v60
	v_lshl_add_u64 v[40:41], s[52:53], 0, v[40:41]
	v_and_b32_e32 v46, 0x4000, v46
	v_mov_b32_e32 v47, v133
	v_mov_b32_e32 v43, v133
	v_lshl_add_u64 v[40:41], v[40:41], 0, v[46:47]
	v_cvt_pk_bf16_f32 v39, v48, v49
	v_lshl_add_u64 v[40:41], v[40:41], 0, v[42:43]
	global_store_dwordx4 v[40:41], v[36:39], off
	v_add_u32_e32 v60, s28, v125
	v_pk_fma_f32 v[32:33], v[16:17], v[32:33], v[50:51]
	v_or_b32_e32 v36, s21, v124
	v_mad_i64_i32 v[40:41], s[4:5], v36, s35, v[44:45]
	v_mov_b64_e32 v[36:37], v[184:185]
	v_mov_b64_e32 v[38:39], v[186:187]
	v_add_co_u32_e32 v40, vcc, s36, v40
	v_pk_mul_f32 v[50:51], v[20:21], v[56:57]
	s_nop 0
	v_addc_co_u32_e32 v41, vcc, 0, v41, vcc
	v_mov_b64_e32 v[46:47], v[224:225]
	v_mov_b64_e32 v[48:49], v[226:227]
	v_mad_i64_i32 v[40:41], s[4:5], v60, s35, v[44:45]
	v_mov_b64_e32 v[64:65], v[148:149]
	v_mov_b64_e32 v[66:67], v[150:151]
	v_pk_fma_f32 v[28:29], v[12:13], v[28:29], v[50:51]
	s_movk_i32 s4, 0x240
	v_lshlrev_b32_e32 v40, 16, v36
	v_and_b32_e32 v41, 0xffff0000, v36
	v_lshlrev_b32_e32 v36, 16, v37
	v_and_b32_e32 v37, 0xffff0000, v37
	v_lshlrev_b32_e32 v42, 16, v46
	v_and_b32_e32 v43, 0xffff0000, v46
	v_pk_mul_f32 v[40:41], v[40:41], v[42:43]
	v_lshlrev_b32_e32 v42, 16, v64
	v_and_b32_e32 v43, 0xffff0000, v64
	v_pk_fma_f32 v[32:33], v[8:9], v[40:41], v[32:33]
	s_nop 0
	v_pk_mul_f32 v[32:33], v[32:33], v[42:43]
; __device__ __forceinline__ const float* inp(const Params& p, int i) { asm volatile("" : "+s"(i)); return p.in[i]; }
; __device__ __forceinline__ unsigned cvt_pk_bf16(float lo, float hi) { f32x2 v = {lo, hi}; bf16x2v b = __builtin_convertvector(v, bf16x2v); return __builtin_bit_cast(unsigned, b); }
; __device__ __forceinline__ float bfv(const u32x4& v, int j) { const unsigned w = v[j >> 1]; return (j & 1) ? bf_hi(w) : bf_lo(w); }
; __device__ void phase_s1(const Params& p, int layer, unsigned char* lds) {
;     ...
; #pragma unroll
;             for (int i = 0; i < 10; ++i) {
;                 const int lrow = l0 - 2 + i;
; #pragma unroll
;                 for (int j = 0; j < 8; ++j) { um2[j] = um1[j]; um1[j] = u0[j]; }
;                 if (lrow >= 0 || (c > 0 && c < NPCH)) {
;                     const bf16_t* rp = proj + (size_t)(row0 + lrow) * PROJ_LD + ch0;
;                     const u32x4 cv = *(const u32x4*)(rp + 1024), xv = *(const u32x4*)(rp + 2048);
; #pragma unroll
;                     for (int j = 0; j < 8; ++j) u0[j] = bfv(cv, j) * bfv(xv, j);
;                 } else if (c == 0) {
; #pragma unroll
;                     for (int j = 0; j < 8; ++j) u0[j] = 0.f;
;                 } else {
;                     const float* hp = inp(p, 2) + (((size_t)layer * 8 + (c - NPCH)) * 2 + (2 + lrow)) * 1024 + ch0;
;                     const f32x4 a = *(const f32x4*)hp, bb = *(const f32x4*)(hp + 4);
; #pragma unroll
;                     for (int j = 0; j < 4; ++j) { u0[j] = a[j]; u0[4 + j] = bb[j]; }
;                 }
;                 if (i >= 2) {
;                     const int l = l0 + i - 2;
;                     const u32x4 bv = *(const u32x4*)(proj + (size_t)(row0 + l) * PROJ_LD + ch0);
;                     float y[8];
; #pragma unroll
;                     for (int j = 0; j < 8; ++j) y[j] = bfv(bv, j) * (w[0][j] * um2[j] + w[1][j] * um1[j] + w[2][j] * u0[j]);
;                     u32x4 pk; pk.x = cvt_pk_bf16(y[0], y[1]); pk.y = cvt_pk_bf16(y[2], y[3]); pk.z = cvt_pk_bf16(y[4], y[5]); pk.w = cvt_pk_bf16(y[6], y[7]);
;                     *(u32x4*)(mix + pg8::img_off(row0 + l, ch0, D_MIX / 64)) = pk;
	v_lshlrev_b32_e32 v42, 16, v47
	v_and_b32_e32 v43, 0xffff0000, v47
	v_pk_mul_f32 v[46:47], v[26:27], v[54:55]
	v_pk_mul_f32 v[42:43], v[36:37], v[42:43]
	v_pk_fma_f32 v[34:35], v[18:19], v[34:35], v[46:47]
	v_lshlrev_b32_e32 v36, 16, v65
	v_and_b32_e32 v37, 0xffff0000, v65
	v_pk_fma_f32 v[34:35], v[10:11], v[42:43], v[34:35]
	v_lshlrev_b32_e32 v46, 16, v48
	v_pk_mul_f32 v[34:35], v[34:35], v[36:37]
	v_lshlrev_b32_e32 v36, 16, v38
	v_and_b32_e32 v37, 0xffff0000, v38
	v_and_b32_e32 v47, 0xffff0000, v48
	v_pk_mul_f32 v[46:47], v[36:37], v[46:47]
	v_lshlrev_b32_e32 v36, 16, v66
	v_and_b32_e32 v37, 0xffff0000, v66
	v_pk_fma_f32 v[28:29], v[4:5], v[46:47], v[28:29]
	v_lshlrev_b32_e32 v38, 16, v49
	v_pk_mul_f32 v[36:37], v[28:29], v[36:37]
	v_lshlrev_b32_e32 v28, 16, v39
	v_and_b32_e32 v29, 0xffff0000, v39
	v_and_b32_e32 v39, 0xffff0000, v49
	v_pk_mul_f32 v[48:49], v[28:29], v[38:39]
	v_pk_mul_f32 v[38:39], v[22:23], v[58:59]
	v_lshlrev_b32_e32 v28, 16, v67
	v_pk_fma_f32 v[30:31], v[14:15], v[30:31], v[38:39]
	v_and_b32_e32 v29, 0xffff0000, v67
	v_pk_fma_f32 v[30:31], v[6:7], v[48:49], v[30:31]
	s_nop 0
	v_pk_mul_f32 v[38:39], v[30:31], v[28:29]
	v_cvt_pk_bf16_f32 v28, v32, v33
	v_cvt_pk_bf16_f32 v29, v34, v35
	v_lshrrev_b32_e32 v32, 8, v60
	v_lshrrev_b32_e32 v35, 3, v60
	v_cvt_pk_bf16_f32 v30, v36, v37
	v_mad_i32_i24 v32, v32, 48, v62
	v_lshlrev_b32_e32 v34, 6, v60
	v_and_or_b32 v35, v35, 14, v114
	v_lshlrev_b32_e32 v36, 2, v60
	v_ashrrev_i32_e32 v33, 31, v32
	v_and_or_b32 v34, v34, s4, v115
	v_lshlrev_b32_e32 v35, 10, v35
	v_and_b32_e32 v36, 32, v36
	v_bitop3_b32 v34, v34, v35, v36 bitop3:0xde
	v_lshlrev_b64 v[32:33], 15, v[32:33]
	v_lshlrev_b32_e32 v36, 7, v60
	v_lshl_add_u64 v[32:33], s[52:53], 0, v[32:33]
	v_and_b32_e32 v36, 0x4000, v36
	v_mov_b32_e32 v37, v133
	v_mov_b32_e32 v35, v133
	v_lshl_add_u64 v[32:33], v[32:33], 0, v[36:37]
	v_cvt_pk_bf16_f32 v31, v38, v39
	v_lshl_add_u64 v[32:33], v[32:33], 0, v[34:35]
	global_store_dwordx4 v[32:33], v[28:31], off
	v_add_u32_e32 v36, s28, v126
	v_mad_i64_i32 v[38:39], s[4:5], v36, s35, v[44:45]
	v_or_b32_e32 v28, s21, v123
	v_mad_i64_i32 v[32:33], s[4:5], v28, s35, v[44:45]
	v_mov_b64_e32 v[28:29], v[188:189]
	v_mov_b64_e32 v[30:31], v[190:191]
	v_add_co_u32_e32 v32, vcc, s36, v32
	v_mov_b64_e32 v[64:65], v[152:153]
	v_mov_b64_e32 v[66:67], v[154:155]
	s_nop 0
	v_addc_co_u32_e32 v33, vcc, 0, v33, vcc
	v_mov_b64_e32 v[32:33], v[228:229]
	v_mov_b64_e32 v[34:35], v[230:231]
	v_pk_mul_f32 v[60:61], v[24:25], v[40:41]
	s_movk_i32 s4, 0x280
	v_pk_fma_f32 v[52:53], v[16:17], v[52:53], v[60:61]
	v_pk_mul_f32 v[60:61], v[20:21], v[46:47]
	v_lshlrev_b32_e32 v37, 2, v36
	v_pk_fma_f32 v[56:57], v[12:13], v[56:57], v[60:61]
	v_and_b32_e32 v37, 32, v37
	v_lshlrev_b32_e32 v38, 16, v28
	v_and_b32_e32 v39, 0xffff0000, v28
	v_lshlrev_b32_e32 v28, 16, v29
	v_and_b32_e32 v29, 0xffff0000, v29
	v_lshlrev_b32_e32 v50, 16, v32
	v_and_b32_e32 v51, 0xffff0000, v32
	v_pk_mul_f32 v[50:51], v[38:39], v[50:51]
	v_lshlrev_b32_e32 v38, 16, v64
	v_and_b32_e32 v39, 0xffff0000, v64
	v_pk_fma_f32 v[52:53], v[8:9], v[50:51], v[52:53]
	v_lshlrev_b32_e32 v32, 16, v33
	v_and_b32_e32 v33, 0xffff0000, v33
	v_pk_mul_f32 v[38:39], v[52:53], v[38:39]
	v_pk_mul_f32 v[52:53], v[28:29], v[32:33]
	v_pk_mul_f32 v[32:33], v[26:27], v[42:43]
	v_lshlrev_b32_e32 v28, 16, v65
	v_pk_fma_f32 v[32:33], v[18:19], v[54:55], v[32:33]
	v_and_b32_e32 v29, 0xffff0000, v65
	v_pk_fma_f32 v[32:33], v[10:11], v[52:53], v[32:33]
	v_lshlrev_b32_e32 v54, 16, v34
	v_pk_mul_f32 v[32:33], v[32:33], v[28:29]
	v_lshlrev_b32_e32 v28, 16, v30
	v_and_b32_e32 v29, 0xffff0000, v30
	v_and_b32_e32 v55, 0xffff0000, v34
	v_pk_mul_f32 v[54:55], v[28:29], v[54:55]
	v_lshlrev_b32_e32 v28, 16, v66
	v_and_b32_e32 v29, 0xffff0000, v66
	v_pk_fma_f32 v[56:57], v[4:5], v[54:55], v[56:57]
	v_lshlrev_b32_e32 v30, 16, v35
	v_pk_mul_f32 v[60:61], v[56:57], v[28:29]
	v_lshlrev_b32_e32 v28, 16, v31
	v_and_b32_e32 v29, 0xffff0000, v31
	v_and_b32_e32 v31, 0xffff0000, v35
	v_pk_mul_f32 v[56:57], v[28:29], v[30:31]
	v_pk_mul_f32 v[30:31], v[22:23], v[48:49]
	v_lshlrev_b32_e32 v28, 16, v67
	v_pk_fma_f32 v[30:31], v[14:15], v[58:59], v[30:31]
	v_and_b32_e32 v29, 0xffff0000, v67
	v_pk_fma_f32 v[30:31], v[6:7], v[56:57], v[30:31]
	v_add_u32_e32 v58, s28, v127
	v_pk_mul_f32 v[34:35], v[30:31], v[28:29]
	v_cvt_pk_bf16_f32 v29, v32, v33
	v_lshrrev_b32_e32 v32, 8, v36
	v_cvt_pk_bf16_f32 v31, v34, v35
	v_mad_i32_i24 v32, v32, 48, v62
	v_lshrrev_b32_e32 v35, 3, v36
	v_ashrrev_i32_e32 v33, 31, v32
	v_lshlrev_b32_e32 v34, 6, v36
	v_and_or_b32 v35, v35, 14, v114
	v_and_or_b32 v34, v34, s4, v115
	v_lshlrev_b32_e32 v35, 10, v35
	v_lshlrev_b64 v[32:33], 15, v[32:33]
	v_lshlrev_b32_e32 v36, 7, v36
	v_bitop3_b32 v34, v34, v35, v37 bitop3:0xde
	v_lshl_add_u64 v[32:33], s[52:53], 0, v[32:33]
	v_and_b32_e32 v36, 0x4000, v36
	v_mov_b32_e32 v37, v133
	v_mov_b32_e32 v35, v133
	v_lshl_add_u64 v[32:33], v[32:33], 0, v[36:37]
	v_cvt_pk_bf16_f32 v28, v38, v39
	v_cvt_pk_bf16_f32 v30, v60, v61
	v_lshl_add_u64 v[32:33], v[32:33], 0, v[34:35]
	global_store_dwordx4 v[32:33], v[28:31], off
	v_mad_i64_i32 v[36:37], s[4:5], v58, s35, v[44:45]
	s_nop 0
	v_or_b32_e32 v28, s21, v125
	v_mad_i64_i32 v[32:33], s[4:5], v28, s35, v[44:45]
	v_mov_b64_e32 v[28:29], v[192:193]
	v_mov_b64_e32 v[30:31], v[194:195]
	v_add_co_u32_e32 v32, vcc, s36, v32
	v_mov_b64_e32 v[64:65], v[156:157]
	v_mov_b64_e32 v[66:67], v[158:159]
	s_nop 0
	v_addc_co_u32_e32 v33, vcc, 0, v33, vcc
	v_mov_b64_e32 v[32:33], v[232:233]
	v_mov_b64_e32 v[34:35], v[234:235]
	v_pk_mul_f32 v[60:61], v[24:25], v[50:51]
	s_movk_i32 s4, 0x2c0
	v_pk_fma_f32 v[40:41], v[16:17], v[40:41], v[60:61]
; __device__ __forceinline__ const float* inp(const Params& p, int i) { asm volatile("" : "+s"(i)); return p.in[i]; }
; __device__ __forceinline__ unsigned cvt_pk_bf16(float lo, float hi) { f32x2 v = {lo, hi}; bf16x2v b = __builtin_convertvector(v, bf16x2v); return __builtin_bit_cast(unsigned, b); }
; __device__ __forceinline__ float bfv(const u32x4& v, int j) { const unsigned w = v[j >> 1]; return (j & 1) ? bf_hi(w) : bf_lo(w); }
; __device__ void phase_s1(const Params& p, int layer, unsigned char* lds) {
;     ...
; #pragma unroll
;             for (int i = 0; i < 10; ++i) {
;                 const int lrow = l0 - 2 + i;
; #pragma unroll
;                 for (int j = 0; j < 8; ++j) { um2[j] = um1[j]; um1[j] = u0[j]; }
;                 if (lrow >= 0 || (c > 0 && c < NPCH)) {
;                     const bf16_t* rp = proj + (size_t)(row0 + lrow) * PROJ_LD + ch0;
;                     const u32x4 cv = *(const u32x4*)(rp + 1024), xv = *(const u32x4*)(rp + 2048);
; #pragma unroll
;                     for (int j = 0; j < 8; ++j) u0[j] = bfv(cv, j) * bfv(xv, j);
;                 } else if (c == 0) {
; #pragma unroll
;                     for (int j = 0; j < 8; ++j) u0[j] = 0.f;
;                 } else {
;                     const float* hp = inp(p, 2) + (((size_t)layer * 8 + (c - NPCH)) * 2 + (2 + lrow)) * 1024 + ch0;
;                     const f32x4 a = *(const f32x4*)hp, bb = *(const f32x4*)(hp + 4);
; #pragma unroll
;                     for (int j = 0; j < 4; ++j) { u0[j] = a[j]; u0[4 + j] = bb[j]; }
;                 }
;                 if (i >= 2) {
;                     const int l = l0 + i - 2;
;                     const u32x4 bv = *(const u32x4*)(proj + (size_t)(row0 + l) * PROJ_LD + ch0);
;                     float y[8];
; #pragma unroll
;                     for (int j = 0; j < 8; ++j) y[j] = bfv(bv, j) * (w[0][j] * um2[j] + w[1][j] * um1[j] + w[2][j] * u0[j]);
;                     u32x4 pk; pk.x = cvt_pk_bf16(y[0], y[1]); pk.y = cvt_pk_bf16(y[2], y[3]); pk.z = cvt_pk_bf16(y[4], y[5]); pk.w = cvt_pk_bf16(y[6], y[7]);
;                     *(u32x4*)(mix + pg8::img_off(row0 + l, ch0, D_MIX / 64)) = pk;
	v_lshlrev_b32_e32 v36, 16, v28
	v_and_b32_e32 v37, 0xffff0000, v28
	v_lshlrev_b32_e32 v28, 16, v29
	v_and_b32_e32 v29, 0xffff0000, v29
	v_lshlrev_b32_e32 v38, 16, v32
	v_and_b32_e32 v39, 0xffff0000, v32
	v_pk_mul_f32 v[36:37], v[36:37], v[38:39]
	v_lshlrev_b32_e32 v38, 16, v64
	v_and_b32_e32 v39, 0xffff0000, v64
	v_pk_fma_f32 v[40:41], v[8:9], v[36:37], v[40:41]
	v_lshlrev_b32_e32 v32, 16, v33
	v_and_b32_e32 v33, 0xffff0000, v33
	v_pk_mul_f32 v[60:61], v[40:41], v[38:39]
	v_pk_mul_f32 v[38:39], v[28:29], v[32:33]
	v_pk_mul_f32 v[32:33], v[26:27], v[52:53]
	v_lshlrev_b32_e32 v28, 16, v65
	v_pk_fma_f32 v[32:33], v[18:19], v[42:43], v[32:33]
	v_and_b32_e32 v29, 0xffff0000, v65
	v_pk_fma_f32 v[32:33], v[10:11], v[38:39], v[32:33]
	v_lshlrev_b32_e32 v40, 16, v34
	v_pk_mul_f32 v[32:33], v[32:33], v[28:29]
	v_lshlrev_b32_e32 v28, 16, v30
	v_and_b32_e32 v29, 0xffff0000, v30
	v_and_b32_e32 v41, 0xffff0000, v34
	v_pk_mul_f32 v[42:43], v[20:21], v[54:55]
	v_pk_mul_f32 v[40:41], v[28:29], v[40:41]
	v_pk_fma_f32 v[42:43], v[12:13], v[46:47], v[42:43]
	v_lshlrev_b32_e32 v28, 16, v66
	v_and_b32_e32 v29, 0xffff0000, v66
	v_pk_fma_f32 v[42:43], v[4:5], v[40:41], v[42:43]
	v_lshlrev_b32_e32 v30, 16, v35
	v_pk_mul_f32 v[46:47], v[42:43], v[28:29]
	v_lshlrev_b32_e32 v28, 16, v31
	v_and_b32_e32 v29, 0xffff0000, v31
	v_and_b32_e32 v31, 0xffff0000, v35
	v_pk_mul_f32 v[42:43], v[28:29], v[30:31]
	v_pk_mul_f32 v[30:31], v[22:23], v[56:57]
	v_lshlrev_b32_e32 v28, 16, v67
	v_pk_fma_f32 v[30:31], v[14:15], v[48:49], v[30:31]
	v_and_b32_e32 v29, 0xffff0000, v67
	v_pk_fma_f32 v[30:31], v[6:7], v[42:43], v[30:31]
	s_nop 0
	v_pk_mul_f32 v[34:35], v[30:31], v[28:29]
	v_cvt_pk_bf16_f32 v29, v32, v33
	v_cvt_pk_bf16_f32 v31, v34, v35
	v_lshrrev_b32_e32 v32, 8, v58
	v_lshrrev_b32_e32 v35, 3, v58
	v_cvt_pk_bf16_f32 v30, v46, v47
	v_mad_i32_i24 v32, v32, 48, v62
	v_lshlrev_b32_e32 v34, 6, v58
	v_and_or_b32 v35, v35, 14, v114
	v_lshlrev_b32_e32 v46, 2, v58
	v_ashrrev_i32_e32 v33, 31, v32
	v_and_or_b32 v34, v34, s4, v115
	v_lshlrev_b32_e32 v35, 10, v35
	v_and_b32_e32 v46, 32, v46
	v_bitop3_b32 v34, v34, v35, v46 bitop3:0xde
	v_lshlrev_b64 v[32:33], 15, v[32:33]
	v_lshlrev_b32_e32 v46, 7, v58
	v_lshl_add_u64 v[32:33], s[52:53], 0, v[32:33]
	v_and_b32_e32 v46, 0x4000, v46
	v_mov_b32_e32 v47, v133
	v_mov_b32_e32 v35, v133
	v_lshl_add_u64 v[32:33], v[32:33], 0, v[46:47]
	v_cvt_pk_bf16_f32 v28, v60, v61
	v_lshl_add_u64 v[32:33], v[32:33], 0, v[34:35]
	global_store_dwordx4 v[32:33], v[28:31], off
	v_add_u32_e32 v58, s28, v128
	v_mad_i64_i32 v[46:47], s[4:5], v58, s35, v[44:45]
	v_or_b32_e32 v28, s21, v126
	v_mad_i64_i32 v[32:33], s[4:5], v28, s35, v[44:45]
	v_mov_b64_e32 v[28:29], v[196:197]
	v_mov_b64_e32 v[30:31], v[198:199]
	v_add_co_u32_e32 v32, vcc, s36, v32
	v_mov_b64_e32 v[64:65], v[72:73]
	v_mov_b64_e32 v[66:67], v[74:75]
	s_nop 0
	v_addc_co_u32_e32 v33, vcc, 0, v33, vcc
	v_mov_b64_e32 v[32:33], v[236:237]
	v_mov_b64_e32 v[34:35], v[238:239]
	v_pk_mul_f32 v[60:61], v[24:25], v[36:37]
	s_movk_i32 s4, 0x300
	v_pk_fma_f32 v[50:51], v[16:17], v[50:51], v[60:61]
	v_lshlrev_b32_e32 v46, 16, v28
	v_and_b32_e32 v47, 0xffff0000, v28
	v_lshlrev_b32_e32 v28, 16, v29
	v_and_b32_e32 v29, 0xffff0000, v29
	v_lshlrev_b32_e32 v48, 16, v32
	v_and_b32_e32 v49, 0xffff0000, v32
	v_pk_mul_f32 v[46:47], v[46:47], v[48:49]
	v_lshlrev_b32_e32 v48, 16, v64
	v_and_b32_e32 v49, 0xffff0000, v64
	v_pk_fma_f32 v[50:51], v[8:9], v[46:47], v[50:51]
	v_lshlrev_b32_e32 v32, 16, v33
	v_and_b32_e32 v33, 0xffff0000, v33
	v_pk_mul_f32 v[60:61], v[50:51], v[48:49]
	v_pk_mul_f32 v[48:49], v[28:29], v[32:33]
	v_pk_mul_f32 v[32:33], v[26:27], v[38:39]
	v_lshlrev_b32_e32 v28, 16, v65
	v_pk_fma_f32 v[32:33], v[18:19], v[52:53], v[32:33]
	v_and_b32_e32 v29, 0xffff0000, v65
	v_pk_fma_f32 v[32:33], v[10:11], v[48:49], v[32:33]
	v_lshlrev_b32_e32 v50, 16, v34
	v_pk_mul_f32 v[32:33], v[32:33], v[28:29]
	v_lshlrev_b32_e32 v28, 16, v30
	v_and_b32_e32 v29, 0xffff0000, v30
	v_and_b32_e32 v51, 0xffff0000, v34
	v_pk_mul_f32 v[52:53], v[20:21], v[40:41]
	v_pk_mul_f32 v[50:51], v[28:29], v[50:51]
	v_pk_fma_f32 v[52:53], v[12:13], v[54:55], v[52:53]
	v_lshlrev_b32_e32 v28, 16, v66
	v_and_b32_e32 v29, 0xffff0000, v66
	v_pk_fma_f32 v[52:53], v[4:5], v[50:51], v[52:53]
	v_lshlrev_b32_e32 v30, 16, v35
	v_pk_mul_f32 v[54:55], v[52:53], v[28:29]
	v_lshlrev_b32_e32 v28, 16, v31
	v_and_b32_e32 v29, 0xffff0000, v31
	v_and_b32_e32 v31, 0xffff0000, v35
	v_pk_mul_f32 v[52:53], v[28:29], v[30:31]
	v_pk_mul_f32 v[30:31], v[22:23], v[42:43]
	v_lshlrev_b32_e32 v28, 16, v67
	v_pk_fma_f32 v[30:31], v[14:15], v[56:57], v[30:31]
	v_and_b32_e32 v29, 0xffff0000, v67
	v_pk_fma_f32 v[30:31], v[6:7], v[52:53], v[30:31]
	v_pk_mul_f32 v[68:69], v[22:23], v[52:53]
	v_pk_mul_f32 v[34:35], v[30:31], v[28:29]
	v_cvt_pk_bf16_f32 v29, v32, v33
	v_cvt_pk_bf16_f32 v31, v34, v35
	v_lshrrev_b32_e32 v32, 8, v58
	v_lshrrev_b32_e32 v35, 3, v58
	v_cvt_pk_bf16_f32 v30, v54, v55
	v_mad_i32_i24 v32, v32, 48, v62
	v_lshlrev_b32_e32 v34, 6, v58
	v_and_or_b32 v35, v35, 14, v114
	v_lshlrev_b32_e32 v54, 2, v58
	v_ashrrev_i32_e32 v33, 31, v32
	v_and_or_b32 v34, v34, s4, v115
	v_lshlrev_b32_e32 v35, 10, v35
	v_and_b32_e32 v54, 32, v54
	v_bitop3_b32 v34, v34, v35, v54 bitop3:0xde
	v_lshlrev_b64 v[32:33], 15, v[32:33]
	v_lshlrev_b32_e32 v54, 7, v58
	v_lshl_add_u64 v[32:33], s[52:53], 0, v[32:33]
	v_and_b32_e32 v54, 0x4000, v54
	v_mov_b32_e32 v55, v133
	v_mov_b32_e32 v35, v133
	v_lshl_add_u64 v[32:33], v[32:33], 0, v[54:55]
	v_cvt_pk_bf16_f32 v28, v60, v61
	v_lshl_add_u64 v[32:33], v[32:33], 0, v[34:35]
	global_store_dwordx4 v[32:33], v[28:31], off
	v_add_u32_e32 v58, s28, v129
; __device__ __forceinline__ const float* inp(const Params& p, int i) { asm volatile("" : "+s"(i)); return p.in[i]; }
; __device__ void phase_s1(const Params& p, int layer, unsigned char* lds) {
;     ...
; #pragma unroll
;             for (int i = 0; i < 10; ++i) {
;                 const int lrow = l0 - 2 + i;
; #pragma unroll
;                 for (int j = 0; j < 8; ++j) { um2[j] = um1[j]; um1[j] = u0[j]; }
;                 if (lrow >= 0 || (c > 0 && c < NPCH)) {
;                     const bf16_t* rp = proj + (size_t)(row0 + lrow) * PROJ_LD + ch0;
;                     const u32x4 cv = *(const u32x4*)(rp + 1024), xv = *(const u32x4*)(rp + 2048);
; #pragma unroll
;                     for (int j = 0; j < 8; ++j) u0[j] = bfv(cv, j) * bfv(xv, j);
;                 } else if (c == 0) {
; #pragma unroll
;                     for (int j = 0; j < 8; ++j) u0[j] = 0.f;
;                 } else {
;                     const float* hp = inp(p, 2) + (((size_t)layer * 8 + (c - NPCH)) * 2 + (2 + lrow)) * 1024 + ch0;
;                     const f32x4 a = *(const f32x4*)hp, bb = *(const f32x4*)(hp + 4);
; #pragma unroll
;                     for (int j = 0; j < 4; ++j) { u0[j] = a[j]; u0[4 + j] = bb[j]; }
;                 }
;                 if (i >= 2) {
;                     const int l = l0 + i - 2;
;                     const u32x4 bv = *(const u32x4*)(proj + (size_t)(row0 + l) * PROJ_LD + ch0);
;                     float y[8];
; #pragma unroll
;                     for (int j = 0; j < 8; ++j) y[j] = bfv(bv, j) * (w[0][j] * um2[j] + w[1][j] * um1[j] + w[2][j] * u0[j]);
;                     u32x4 pk; pk.x = cvt_pk_bf16(y[0], y[1]); pk.y = cvt_pk_bf16(y[2], y[3]); pk.z = cvt_pk_bf16(y[4], y[5]); pk.w = cvt_pk_bf16(y[6], y[7]);
;                     *(u32x4*)(mix + pg8::img_off(row0 + l, ch0, D_MIX / 64)) = pk;
;                     if (last_chunk && l >= 62) {
;                         float* op = (c < NPCH) ? p.out + O_SC_P + ((size_t)layer * 2 + (l - 62)) * 1024 + ch0
;                                                : p.out + O_SC_S + (((size_t)layer * 8 + (c - NPCH)) * 2 + (l - 62)) * 1024 + ch0;
;                         *(f32x4*)op = (f32x4){u0[0], u0[1], u0[2], u0[3]}; *(f32x4*)(op + 4) = (f32x4){u0[4], u0[5], u0[6], u0[7]};
;                     }
	v_mad_i64_i32 v[54:55], s[4:5], v58, s35, v[44:45]
	v_or_b32_e32 v28, s21, v127
	v_mad_i64_i32 v[32:33], s[4:5], v28, s35, v[44:45]
	v_mov_b64_e32 v[28:29], v[200:201]
	v_mov_b64_e32 v[30:31], v[202:203]
	v_add_co_u32_e32 v32, vcc, s36, v32
	v_mov_b64_e32 v[64:65], v[76:77]
	v_mov_b64_e32 v[66:67], v[78:79]
	s_nop 0
	v_addc_co_u32_e32 v33, vcc, 0, v33, vcc
	v_mov_b64_e32 v[32:33], v[240:241]
	v_mov_b64_e32 v[34:35], v[242:243]
	v_lshrrev_b32_e32 v54, 8, v58
	v_mad_i32_i24 v54, v54, 48, v62
	v_lshrrev_b32_e32 v57, 3, v58
	v_ashrrev_i32_e32 v55, 31, v54
	v_lshlrev_b32_e32 v56, 6, v58
	v_and_or_b32 v57, v57, 14, v114
	s_movk_i32 s4, 0x340
	v_lshlrev_b32_e32 v59, 2, v58
	v_and_or_b32 v56, v56, s4, v115
	v_lshlrev_b32_e32 v57, 10, v57
	v_and_b32_e32 v59, 32, v59
	v_lshlrev_b64 v[54:55], 15, v[54:55]
	v_lshlrev_b32_e32 v58, 7, v58
	v_bitop3_b32 v56, v56, v57, v59 bitop3:0xde
	v_lshl_add_u64 v[54:55], s[52:53], 0, v[54:55]
	v_and_b32_e32 v58, 0x4000, v58
	v_mov_b32_e32 v59, v133
	v_mov_b32_e32 v57, v133
	v_lshl_add_u64 v[54:55], v[54:55], 0, v[58:59]
	v_lshl_add_u64 v[60:61], v[54:55], 0, v[56:57]
	v_or_b32_e32 v54, s21, v128
	v_mad_i64_i32 v[58:59], s[4:5], v54, s35, v[44:45]
	v_pk_fma_f32 v[42:43], v[14:15], v[42:43], v[68:69]
	v_lshlrev_b32_e32 v54, 16, v31
	v_and_b32_e32 v55, 0xffff0000, v31
	v_lshlrev_b32_e32 v56, 16, v35
	v_and_b32_e32 v57, 0xffff0000, v35
	v_pk_mul_f32 v[54:55], v[54:55], v[56:57]
	v_lshlrev_b32_e32 v56, 16, v67
	v_and_b32_e32 v57, 0xffff0000, v67
	v_pk_fma_f32 v[42:43], v[6:7], v[54:55], v[42:43]
	v_and_b32_e32 v35, 0xffff0000, v66
	v_pk_mul_f32 v[42:43], v[42:43], v[56:57]
	v_lshlrev_b32_e32 v56, 16, v34
	v_cvt_pk_bf16_f32 v31, v42, v43
	v_lshlrev_b32_e32 v42, 16, v30
	v_and_b32_e32 v43, 0xffff0000, v30
	v_and_b32_e32 v57, 0xffff0000, v34
	v_pk_mul_f32 v[42:43], v[42:43], v[56:57]
	v_pk_mul_f32 v[56:57], v[20:21], v[50:51]
	v_lshlrev_b32_e32 v34, 16, v66
	v_pk_fma_f32 v[40:41], v[12:13], v[40:41], v[56:57]
	v_pk_mul_f32 v[56:57], v[26:27], v[48:49]
	v_pk_fma_f32 v[40:41], v[4:5], v[42:43], v[40:41]
	v_pk_fma_f32 v[38:39], v[18:19], v[38:39], v[56:57]
	v_pk_mul_f32 v[34:35], v[40:41], v[34:35]
	v_lshlrev_b32_e32 v40, 16, v33
	v_cvt_pk_bf16_f32 v30, v34, v35
	v_lshlrev_b32_e32 v34, 16, v29
	v_and_b32_e32 v35, 0xffff0000, v29
	v_and_b32_e32 v41, 0xffff0000, v33
	v_pk_mul_f32 v[40:41], v[34:35], v[40:41]
	v_lshlrev_b32_e32 v34, 16, v65
	v_and_b32_e32 v35, 0xffff0000, v65
	v_pk_fma_f32 v[38:39], v[10:11], v[40:41], v[38:39]
	v_and_b32_e32 v33, 0xffff0000, v64
	v_pk_mul_f32 v[34:35], v[38:39], v[34:35]
	v_lshlrev_b32_e32 v38, 16, v32
	v_cvt_pk_bf16_f32 v29, v34, v35
	v_lshlrev_b32_e32 v34, 16, v28
	v_and_b32_e32 v35, 0xffff0000, v28
	v_and_b32_e32 v39, 0xffff0000, v32
	v_pk_mul_f32 v[56:57], v[34:35], v[38:39]
	v_pk_mul_f32 v[34:35], v[24:25], v[46:47]
	v_lshlrev_b32_e32 v32, 16, v64
	v_pk_fma_f32 v[34:35], v[16:17], v[36:37], v[34:35]
	s_nop 0
	v_pk_fma_f32 v[34:35], v[8:9], v[56:57], v[34:35]
	s_nop 0
	v_pk_mul_f32 v[32:33], v[34:35], v[32:33]
	s_nop 0
	v_cvt_pk_bf16_f32 v28, v32, v33
	v_add_co_u32_e32 v32, vcc, s36, v58
	global_store_dwordx4 v[60:61], v[28:31], off
	s_nop 0
	v_addc_co_u32_e32 v33, vcc, 0, v59, vcc
	v_mov_b64_e32 v[28:29], v[204:205]
	v_mov_b64_e32 v[30:31], v[206:207]
	v_mov_b64_e32 v[34:35], v[244:245]
	v_mov_b64_e32 v[36:37], v[246:247]
	v_pk_mul_f32 v[60:61], v[24:25], v[56:57]
	v_lshlrev_b32_e32 v32, 16, v28
	v_and_b32_e32 v33, 0xffff0000, v28
	v_lshlrev_b32_e32 v38, 16, v34
	v_and_b32_e32 v39, 0xffff0000, v34
	v_lshlrev_b32_e32 v28, 16, v29
	v_and_b32_e32 v29, 0xffff0000, v29
	v_lshlrev_b32_e32 v34, 16, v35
	v_and_b32_e32 v35, 0xffff0000, v35
	v_pk_mul_f32 v[32:33], v[32:33], v[38:39]
	v_pk_mul_f32 v[34:35], v[28:29], v[34:35]
	v_lshlrev_b32_e32 v28, 16, v30
	v_and_b32_e32 v29, 0xffff0000, v30
	v_lshlrev_b32_e32 v38, 16, v36
	v_and_b32_e32 v39, 0xffff0000, v36
	v_lshlrev_b32_e32 v30, 16, v31
	v_and_b32_e32 v31, 0xffff0000, v31
	v_lshlrev_b32_e32 v36, 16, v37
	v_and_b32_e32 v37, 0xffff0000, v37
	v_pk_mul_f32 v[30:31], v[30:31], v[36:37]
	v_mad_i64_i32 v[36:37], s[4:5], v63, s35, v[44:45]
	v_pk_mul_f32 v[28:29], v[28:29], v[38:39]
	v_mov_b64_e32 v[36:37], v[80:81]
	v_mov_b64_e32 v[38:39], v[82:83]
	v_pk_fma_f32 v[46:47], v[16:17], v[46:47], v[60:61]
	s_movk_i32 s4, 0x380
	v_pk_fma_f32 v[46:47], v[8:9], v[32:33], v[46:47]
	v_lshlrev_b32_e32 v58, 16, v36
	v_and_b32_e32 v59, 0xffff0000, v36
	v_pk_mul_f32 v[46:47], v[46:47], v[58:59]
	v_pk_mul_f32 v[58:59], v[26:27], v[40:41]
	v_lshlrev_b32_e32 v36, 16, v37
	v_pk_fma_f32 v[48:49], v[18:19], v[48:49], v[58:59]
	v_pk_mul_f32 v[58:59], v[20:21], v[42:43]
	v_and_b32_e32 v37, 0xffff0000, v37
	v_pk_fma_f32 v[48:49], v[10:11], v[34:35], v[48:49]
	v_pk_fma_f32 v[50:51], v[12:13], v[50:51], v[58:59]
	v_pk_mul_f32 v[48:49], v[48:49], v[36:37]
	v_lshlrev_b32_e32 v36, 16, v38
	v_and_b32_e32 v37, 0xffff0000, v38
	v_pk_fma_f32 v[50:51], v[4:5], v[28:29], v[50:51]
	s_nop 0
	v_pk_mul_f32 v[50:51], v[50:51], v[36:37]
	v_lshlrev_b32_e32 v36, 16, v39
	v_and_b32_e32 v37, 0xffff0000, v39
	v_pk_mul_f32 v[38:39], v[22:23], v[54:55]
	s_nop 0
	v_pk_fma_f32 v[38:39], v[14:15], v[52:53], v[38:39]
	s_nop 0
	v_pk_fma_f32 v[38:39], v[6:7], v[30:31], v[38:39]
	s_nop 0
	v_pk_mul_f32 v[52:53], v[38:39], v[36:37]
	v_cvt_pk_bf16_f32 v36, v46, v47
	v_cvt_pk_bf16_f32 v37, v48, v49
	v_lshrrev_b32_e32 v46, 8, v63
	v_lshrrev_b32_e32 v49, 3, v63
	v_cvt_pk_bf16_f32 v38, v50, v51
	v_mad_i32_i24 v46, v46, 48, v62
	v_lshlrev_b32_e32 v48, 6, v63
	v_and_or_b32 v49, v49, 14, v114
	v_lshlrev_b32_e32 v50, 2, v63
	v_ashrrev_i32_e32 v47, 31, v46
	v_and_or_b32 v48, v48, s4, v115
	v_lshlrev_b32_e32 v49, 10, v49
	v_and_b32_e32 v50, 32, v50
	v_bitop3_b32 v48, v48, v49, v50 bitop3:0xde
	v_lshlrev_b64 v[46:47], 15, v[46:47]
	v_lshlrev_b32_e32 v50, 7, v63
	v_lshl_add_u64 v[46:47], s[52:53], 0, v[46:47]
	v_and_b32_e32 v50, 0x4000, v50
	v_mov_b32_e32 v51, v133
	v_mov_b32_e32 v49, v133
	v_lshl_add_u64 v[46:47], v[46:47], 0, v[50:51]
	v_cvt_pk_bf16_f32 v39, v52, v53
	v_lshl_add_u64 v[46:47], v[46:47], 0, v[48:49]
	s_and_b64 s[52:53], s[60:61], s[82:83]
	global_store_dwordx4 v[46:47], v[36:39], off
	s_and_saveexec_b64 s[4:5], s[52:53]
	s_cbranch_execz .LBB0_347
	s_and_b64 s[52:53], s[64:65], exec
	s_mov_b32 s29, 0x4400000
	s_cselect_b32 s29, s29, 0x461c000
	s_cselect_b32 s39, s75, s67
	s_cselect_b32 s52, s74, s66
	s_add_u32 s29, s8, s29
	s_addc_u32 s53, s9, 0
	s_add_u32 s52, s29, s52
	s_addc_u32 s53, s53, s39
	v_lshl_add_u64 v[36:37], v[132:133], 2, s[52:53]
	global_store_dwordx4 v[36:37], v[32:35], off
	global_store_dwordx4 v[36:37], v[28:31], off offset:16
; __device__ __forceinline__ u32x4 fetch_xbc8(const bf16_t* proj, const float* hist, int c, int lrow, int col) {
;     if (lrow >= 0 || (c > 0 && c < NPCH)) return *(const u32x4*)(proj + (size_t)(c * 64 + lrow) * PROJ_LD + 5120 + col);
;     if (c == 0) return (u32x4){0u, 0u, 0u, 0u};
;     const float* h = hist + ((size_t)(c - NPCH) * 3 + (3 + lrow)) * 4096 + col;
;     const f32x4 a = *(const f32x4*)h, b = *(const f32x4*)(h + 4);
; __device__ void phase_s1(const Params& p, int layer, unsigned char* lds) {
;     ...
;                     const bf16_t* rp = proj + (size_t)(row0 + lrow) * PROJ_LD + ch0;
;                     const u32x4 cv = *(const u32x4*)(rp + 1024), xv = *(const u32x4*)(rp + 2048);
; #pragma unroll
;                     for (int j = 0; j < 8; ++j) u0[j] = bfv(cv, j) * bfv(xv, j);
;                 } else if (c == 0) {
; #pragma unroll
;                     for (int j = 0; j < 8; ++j) u0[j] = 0.f;
;                 } else {
;                     const float* hp = inp(p, 2) + (((size_t)layer * 8 + (c - NPCH)) * 2 + (2 + lrow)) * 1024 + ch0;
;                     const f32x4 a = *(const f32x4*)hp, bb = *(const f32x4*)(hp + 4);
; #pragma unroll
;                     for (int j = 0; j < 4; ++j) { u0[j] = a[j]; u0[4 + j] = bb[j]; }
;                 }
;                 if (i >= 2) {
;                     const int l = l0 + i - 2;
;                     const u32x4 bv = *(const u32x4*)(proj + (size_t)(row0 + l) * PROJ_LD + ch0);
;                     float y[8];
; #pragma unroll
;                     for (int j = 0; j < 8; ++j) y[j] = bfv(bv, j) * (w[0][j] * um2[j] + w[1][j] * um1[j] + w[2][j] * u0[j]);
;                     u32x4 pk; pk.x = cvt_pk_bf16(y[0], y[1]); pk.y = cvt_pk_bf16(y[2], y[3]); pk.z = cvt_pk_bf16(y[4], y[5]); pk.w = cvt_pk_bf16(y[6], y[7]);
;                     *(u32x4*)(mix + pg8::img_off(row0 + l, ch0, D_MIX / 64)) = pk;
;                     if (last_chunk && l >= 62) {
;                         float* op = (c < NPCH) ? p.out + O_SC_P + ((size_t)layer * 2 + (l - 62)) * 1024 + ch0
;                                                : p.out + O_SC_S + (((size_t)layer * 8 + (c - NPCH)) * 2 + (l - 62)) * 1024 + ch0;
;                         *(f32x4*)op = (f32x4){u0[0], u0[1], u0[2], u0[3]}; *(f32x4*)(op + 4) = (f32x4){u0[4], u0[5], u0[6], u0[7]};
;                     }
.LBB0_347:
	s_or_b64 exec, exec, s[4:5]
	v_or_b32_e32 v36, s21, v129
	v_mad_i64_i32 v[48:49], s[4:5], v36, s35, v[44:45]
	v_mov_b64_e32 v[36:37], v[208:209]
	v_mov_b64_e32 v[38:39], v[210:211]
	v_add_u32_e32 v52, s28, v131
	v_add_co_u32_e32 v48, vcc, 0x1000, v48
	v_mad_i64_i32 v[44:45], s[4:5], v52, s35, v[44:45]
	s_nop 0
	v_addc_co_u32_e32 v49, vcc, 0, v49, vcc
	v_mov_b64_e32 v[44:45], v[84:85]
	v_mov_b64_e32 v[46:47], v[86:87]
	v_pk_mul_f32 v[20:21], v[20:21], v[28:29]
	v_mov_b64_e32 v[48:49], v[140:141]
	v_mov_b64_e32 v[50:51], v[142:143]
	v_pk_fma_f32 v[20:21], v[12:13], v[42:43], v[20:21]
	v_lshrrev_b32_e32 v12, 8, v52
	v_pk_mul_f32 v[24:25], v[24:25], v[32:33]
	v_pk_mul_f32 v[22:23], v[22:23], v[30:31]
	v_lshlrev_b32_e32 v13, 6, v52
	v_mad_i32_i24 v12, v12, 48, v62
	v_pk_fma_f32 v[24:25], v[16:17], v[56:57], v[24:25]
	v_pk_fma_f32 v[22:23], v[14:15], v[54:55], v[22:23]
	v_lshrrev_b32_e32 v14, 3, v52
	v_and_or_b32 v17, v13, s15, v115
	v_ashrrev_i32_e32 v13, 31, v12
	v_readlane_b32 s4, v252, 21
	v_lshlrev_b32_e32 v15, 2, v52
	v_lshlrev_b32_e32 v16, 7, v52
	v_and_or_b32 v14, v14, 14, v114
	v_lshlrev_b64 v[12:13], 15, v[12:13]
	v_readlane_b32 s5, v252, 22
	v_mov_b32_e32 v31, v133
	v_and_b32_e32 v15, 32, v15
	v_and_b32_e32 v30, 0x4000, v16
	v_lshlrev_b32_e32 v14, 10, v14
	v_lshl_add_u64 v[12:13], s[4:5], 0, v[12:13]
	v_pk_mul_f32 v[26:27], v[26:27], v[34:35]
	v_mov_b32_e32 v29, v133
	v_bitop3_b32 v28, v17, v14, v15 bitop3:0xde
	v_lshl_add_u64 v[12:13], v[12:13], 0, v[30:31]
	v_pk_fma_f32 v[26:27], v[18:19], v[40:41], v[26:27]
	v_lshl_add_u64 v[28:29], v[12:13], 0, v[28:29]
	s_and_b64 s[28:29], s[82:83], s[84:85]
	v_lshlrev_b32_e32 v12, 16, v36
	v_and_b32_e32 v13, 0xffff0000, v36
	v_lshlrev_b32_e32 v14, 16, v37
	v_and_b32_e32 v15, 0xffff0000, v37
	v_lshlrev_b32_e32 v30, 16, v38
	v_and_b32_e32 v31, 0xffff0000, v38
	v_lshlrev_b32_e32 v32, 16, v39
	v_and_b32_e32 v33, 0xffff0000, v39
	v_lshlrev_b32_e32 v34, 16, v44
	v_and_b32_e32 v35, 0xffff0000, v44
	v_lshlrev_b32_e32 v36, 16, v45
	v_and_b32_e32 v37, 0xffff0000, v45
	v_lshlrev_b32_e32 v16, 16, v48
	v_and_b32_e32 v17, 0xffff0000, v48
	v_lshlrev_b32_e32 v18, 16, v49
	v_and_b32_e32 v19, 0xffff0000, v49
	v_lshlrev_b32_e32 v42, 16, v50
	v_and_b32_e32 v43, 0xffff0000, v50
	v_lshlrev_b32_e32 v44, 16, v51
	v_and_b32_e32 v45, 0xffff0000, v51
	v_pk_mul_f32 v[16:17], v[12:13], v[16:17]
	v_pk_mul_f32 v[18:19], v[14:15], v[18:19]
	v_pk_mul_f32 v[12:13], v[30:31], v[42:43]
	v_pk_mul_f32 v[14:15], v[32:33], v[44:45]
	v_lshlrev_b32_e32 v38, 16, v46
	v_and_b32_e32 v39, 0xffff0000, v46
	v_lshlrev_b32_e32 v40, 16, v47
	v_and_b32_e32 v41, 0xffff0000, v47
	v_pk_fma_f32 v[8:9], v[8:9], v[16:17], v[24:25]
	v_pk_fma_f32 v[10:11], v[10:11], v[18:19], v[26:27]
	v_pk_fma_f32 v[4:5], v[4:5], v[12:13], v[20:21]
	v_pk_fma_f32 v[6:7], v[6:7], v[14:15], v[22:23]
	v_pk_mul_f32 v[8:9], v[8:9], v[34:35]
	v_pk_mul_f32 v[10:11], v[10:11], v[36:37]
	v_pk_mul_f32 v[20:21], v[4:5], v[38:39]
	v_pk_mul_f32 v[22:23], v[6:7], v[40:41]
	v_cvt_pk_bf16_f32 v4, v8, v9
	v_cvt_pk_bf16_f32 v5, v10, v11
	v_cvt_pk_bf16_f32 v6, v20, v21
	v_cvt_pk_bf16_f32 v7, v22, v23
	global_store_dwordx4 v[28:29], v[4:7], off
	s_and_saveexec_b64 s[4:5], s[28:29]
	s_cbranch_execz .LBB0_349
	s_and_b64 s[28:29], s[64:65], exec
	s_mov_b32 s28, 0x4400000
	s_cselect_b32 s28, s28, 0x461c000
	s_cselect_b32 s29, s75, s67
	s_cselect_b32 s39, s74, s66
	s_add_u32 s28, s8, s28
	s_addc_u32 s52, s9, 0
	s_add_u32 s28, s28, s39
	s_addc_u32 s29, s52, s29
	v_lshl_add_u64 v[4:5], s[28:29], 0, v[90:91]
	v_lshl_add_u64 v[4:5], v[132:133], 2, v[4:5]
	global_store_dwordx4 v[4:5], v[16:19], off
	global_store_dwordx4 v[4:5], v[12:15], off offset:16
.LBB0_349:
	s_or_b64 exec, exec, s[4:5]
	s_barrier
.LBB0_350:
	s_andn2_saveexec_b64 s[66:67], s[80:81]
	s_cbranch_execz .LBB0_328
	s_add_i32 s4, s87, -1
	s_cmpk_gt_u32 s4, 0x7e
	v_lshl_add_u32 v4, s2, 8, v117
	v_lshl_add_u32 v5, s2, 7, v116
	s_cselect_b64 s[4:5], -1, 0
	s_cmp_gt_u32 s86, 7
	v_cndmask_b32_e64 v48, v5, v4, s[56:57]
	s_cselect_b64 s[28:29], -1, 0
	s_mul_i32 s39, s87, 3
	s_add_i32 s80, s39, 0xfffffe80
	v_ashrrev_i32_e32 v49, 31, v48
	s_xor_b64 s[52:53], s[58:59], -1
	v_cndmask_b32_e64 v4, 0, 1, s[28:29]
	s_ashr_i32 s81, s80, 31
	v_lshl_add_u64 v[16:17], v[48:49], 2, s[72:73]
	s_and_b64 s[4:5], s[52:53], s[4:5]
	v_cmp_ne_u32_e64 s[64:65], 1, v4
	s_and_saveexec_b64 s[28:29], s[4:5]
	s_xor_b64 s[28:29], exec, s[28:29]
	s_cbranch_execz .LBB0_354
	v_mov_b32_e32 v7, 0
	s_and_b64 vcc, exec, s[64:65]
	v_mov_b32_e32 v6, 0
	v_mov_b32_e32 v5, 0
	v_mov_b32_e32 v4, 0
	s_cbranch_vccnz .LBB0_354
	s_lshl_b64 s[52:53], s[80:81], 14
	v_lshl_add_u64 v[8:9], v[16:17], 0, s[52:53]
	global_load_dwordx4 v[4:7], v[8:9], off
	s_nop 0
	global_load_dwordx4 v[8:11], v[8:9], off offset:16
	s_waitcnt vmcnt(1)
	v_cvt_pk_bf16_f32 v4, v4, v5
	v_cvt_pk_bf16_f32 v5, v6, v7
	s_waitcnt vmcnt(0)
	v_cvt_pk_bf16_f32 v6, v8, v9
	v_cvt_pk_bf16_f32 v7, v10, v11

; __device__ __forceinline__ const float* inp(const Params& p, int i) { asm volatile("" : "+s"(i)); return p.in[i]; }
; __device__ void phase_s1(const Params& p, int layer, unsigned char* lds) {
;     ...
;         }
;         __syncthreads();
;         if (tid < 384) {
;             const int rr = tid & 7, cg = tid >> 3, l0 = rr * 8;
;             const int col = (cg < 32) ? g * 256 + cg * 8 : 2048 + g * 128 + (cg - 32) * 8;
;             u32x4 rows[11];
; #pragma unroll
;             for (int i = 0; i < 11; ++i) rows[i] = fetch_xbc8(proj, hist, c, l0 - 3 + i, col);
;             const float* cw = inp(p, 12) + (size_t)layer * 4 * 4096 + col; const float* cb = inp(p, 13) + (size_t)layer * 4096 + col;
;             float w[4][8], b[8];
; #pragma unroll
;             for (int k = 0; k < 4; ++k) { const f32x4 a = *(const f32x4*)(cw + k * 4096), bb = *(const f32x4*)(cw + k * 4096 + 4);
; #pragma unroll
;                 for (int j = 0; j < 4; ++j) { w[k][j] = a[j]; w[k][4 + j] = bb[j]; } }
;             { const f32x4 a = *(const f32x4*)cb, bb = *(const f32x4*)(cb + 4);
; #pragma unroll
;               for (int j = 0; j < 4; ++j) { b[j] = a[j]; b[4 + j] = bb[j]; } }
;             float sc[8];
; #pragma unroll
;             for (int i = 0; i < 8; ++i) sc[i] = (cg < 32) ? s_w[(cg >> 3) * 64 + l0 + i] : 1.f;
.LBB0_366:
	s_or_b64 exec, exec, s[4:5]
	v_readlane_b32 s4, v252, 19
	v_readlane_b32 s5, v252, 20
	v_or_b32_e32 v16, s21, v112
	v_lshlrev_b64 v[30:31], 1, v[48:49]
	v_mov_b64_e32 v[28:29], s[4:5]
	v_mad_i64_i32 v[16:17], s[4:5], v16, s35, v[28:29]
	v_lshl_add_u64 v[16:17], v[16:17], 0, v[30:31]
	v_or_b32_e32 v18, s21, v124
	v_add_co_u32_e32 v16, vcc, 0x2000, v16
	v_mad_i64_i32 v[18:19], s[4:5], v18, s35, v[28:29]
	s_nop 0
	v_addc_co_u32_e32 v17, vcc, 0, v17, vcc
	v_lshl_add_u64 v[18:19], v[18:19], 0, v[30:31]
	v_or_b32_e32 v24, s21, v123
	v_add_co_u32_e32 v20, vcc, 0x2000, v18
	v_mad_i64_i32 v[24:25], s[4:5], v24, s35, v[28:29]
	s_nop 0
	v_addc_co_u32_e32 v21, vcc, 0, v19, vcc
	v_lshl_add_u64 v[24:25], v[24:25], 0, v[30:31]
	v_or_b32_e32 v26, s21, v125
	v_add_co_u32_e32 v24, vcc, 0x2000, v24
	v_mad_i64_i32 v[26:27], s[4:5], v26, s35, v[28:29]
	s_nop 0
	v_addc_co_u32_e32 v25, vcc, 0, v25, vcc
	v_lshl_add_u64 v[26:27], v[26:27], 0, v[30:31]
	v_or_b32_e32 v36, s21, v126
	v_add_co_u32_e32 v32, vcc, 0x2000, v26
	v_mad_i64_i32 v[36:37], s[4:5], v36, s35, v[28:29]
	s_nop 0
	v_addc_co_u32_e32 v33, vcc, 0, v27, vcc
	v_lshl_add_u64 v[36:37], v[36:37], 0, v[30:31]
	v_or_b32_e32 v38, s21, v127
	v_add_co_u32_e32 v36, vcc, 0x2000, v36
	v_mad_i64_i32 v[38:39], s[4:5], v38, s35, v[28:29]
	s_nop 0
	v_addc_co_u32_e32 v37, vcc, 0, v37, vcc
	v_lshl_add_u64 v[38:39], v[38:39], 0, v[30:31]
	v_or_b32_e32 v44, s21, v128
	v_add_co_u32_e32 v38, vcc, 0x2000, v38
	v_mad_i64_i32 v[44:45], s[4:5], v44, s35, v[28:29]
	s_nop 0
	v_addc_co_u32_e32 v39, vcc, 0, v39, vcc
	v_lshl_add_u64 v[44:45], v[44:45], 0, v[30:31]
	v_or_b32_e32 v46, s21, v129
	v_add_co_u32_e32 v44, vcc, 0x2000, v44
	v_mad_i64_i32 v[28:29], s[4:5], v46, s35, v[28:29]
	s_nop 0
	v_addc_co_u32_e32 v45, vcc, 0, v45, vcc
	v_lshl_add_u64 v[28:29], v[28:29], 0, v[30:31]
	v_add_co_u32_e32 v28, vcc, 0x2000, v28
	s_mov_b32 s4, 12
	s_nop 0
	v_addc_co_u32_e32 v29, vcc, 0, v29, vcc
	global_load_dwordx4 v[16:19], v[16:17], off offset:2048
	s_nop 0
	global_load_dwordx4 v[20:23], v[20:21], off offset:2048
	s_nop 0
	global_load_dwordx4 v[24:27], v[24:25], off offset:2048
	s_nop 0
	global_load_dwordx4 v[32:35], v[32:33], off offset:2048
	s_nop 0
	global_load_dwordx4 v[40:43], v[36:37], off offset:2048
	s_nop 0
	global_load_dwordx4 v[36:39], v[38:39], off offset:2048
	s_nop 0
	global_load_dwordx4 v[44:47], v[44:45], off offset:2048
	s_nop 0
	global_load_dwordx4 v[28:31], v[28:29], off offset:2048
	s_ashr_i32 s5, s4, 31
	s_lshl_b64 s[4:5], s[4:5], 3
	s_add_u32 s4, s0, s4
	s_addc_u32 s5, s1, s5
	s_load_dwordx2 s[4:5], s[4:5], 0x0
	s_mov_b32 s28, 13
	v_lshlrev_b64 v[64:65], 2, v[48:49]
	s_movk_i32 s21, 0x4000
	s_waitcnt lgkmcnt(0)
	s_add_u32 s4, s4, s76
	s_addc_u32 s5, s5, s77
	s_ashr_i32 s29, s28, 31
	s_lshl_b64 s[28:29], s[28:29], 3
	s_add_u32 s28, s0, s28
	s_addc_u32 s29, s1, s29
	s_load_dwordx2 s[28:29], s[28:29], 0x0
	v_lshl_add_u64 v[60:61], s[4:5], 0, v[64:65]
	v_add_co_u32_e32 v50, vcc, s21, v60
	s_mov_b32 s21, 0x8000
	s_waitcnt lgkmcnt(0)
	s_add_u32 s4, s28, s78
	s_addc_u32 s5, s29, s79
	s_mov_b64 s[28:29], 0x4000
	v_addc_co_u32_e32 v51, vcc, 0, v61, vcc
	v_lshl_add_u64 v[48:49], v[60:61], 0, s[28:29]
	s_mov_b64 s[28:29], 0x8000
	v_add_co_u32_e32 v58, vcc, s21, v60
	v_lshl_add_u64 v[56:57], v[60:61], 0, s[28:29]
	s_nop 0
	v_addc_co_u32_e32 v59, vcc, 0, v61, vcc
	s_mov_b64 s[28:29], 0xc000
	global_load_dwordx4 v[52:55], v[60:61], off offset:16
	global_load_dwordx4 v[72:75], v[60:61], off
	v_lshl_add_u64 v[62:63], v[60:61], 0, s[28:29]
	v_add_co_u32_e32 v60, vcc, 0xc000, v60
	v_lshl_add_u64 v[84:85], s[4:5], 0, v[64:65]
	s_nop 0
	v_addc_co_u32_e32 v61, vcc, 0, v61, vcc
	global_load_dwordx4 v[68:71], v[50:51], off
	s_nop 0
	global_load_dwordx4 v[48:51], v[48:49], off offset:16
	s_nop 0
	global_load_dwordx4 v[76:79], v[58:59], off
	s_nop 0
	global_load_dwordx4 v[56:59], v[56:57], off offset:16
	s_nop 0
	global_load_dwordx4 v[80:83], v[60:61], off
	s_nop 0
	global_load_dwordx4 v[60:63], v[62:63], off offset:16
	s_nop 0
	global_load_dwordx4 v[64:67], v[84:85], off offset:16
	s_nop 0
	global_load_dwordx4 v[84:87], v[84:85], off
	s_waitcnt lgkmcnt(0)
	s_barrier
	v_mov_b32_e32 v103, 1.0
	v_mov_b32_e32 v102, 1.0
	s_and_saveexec_b64 s[4:5], s[56:57]
	ds_read_b32 v102, v119 offset:55296
	s_or_b64 exec, exec, s[4:5]
	s_and_saveexec_b64 s[4:5], s[56:57]
	ds_read_b32 v103, v119 offset:55300
	s_or_b64 exec, exec, s[4:5]
	v_mov_b32_e32 v101, 1.0
	v_mov_b32_e32 v100, 1.0
	s_and_saveexec_b64 s[4:5], s[56:57]
	ds_read_b32 v100, v119 offset:55304
	s_or_b64 exec, exec, s[4:5]
	s_and_saveexec_b64 s[4:5], s[56:57]
	ds_read_b32 v101, v119 offset:55308
	s_or_b64 exec, exec, s[4:5]
	v_mov_b32_e32 v105, 1.0
	v_mov_b32_e32 v104, 1.0
	s_and_saveexec_b64 s[4:5], s[56:57]
	ds_read_b32 v104, v119 offset:55312
	s_or_b64 exec, exec, s[4:5]
	s_and_saveexec_b64 s[4:5], s[56:57]
	ds_read_b32 v105, v119 offset:55316
	s_or_b64 exec, exec, s[4:5]
	v_mov_b32_e32 v107, 1.0
	v_mov_b32_e32 v106, 1.0
	s_and_saveexec_b64 s[4:5], s[56:57]
	ds_read_b32 v106, v119 offset:55320
	s_or_b64 exec, exec, s[4:5]
	s_and_saveexec_b64 s[4:5], s[56:57]
	s_cbranch_execz .LBB0_327
	ds_read_b32 v107, v119 offset:55324
	s_branch .LBB0_327
